# speedup vs baseline: 1.0191x; 1.0149x over previous
; __device__ __forceinline__ void attn_unit(const bf16* __restrict__ U, const bf16* __restrict__ VT, bf16* __restrict__ Y, int b, int qb, LAS float* red, int wave, int lane) {
;     const int h = wave, fr = lane & 15, fq = lane >> 4;
;     const size_t rowq = (size_t)b * SEQ + (size_t)qb * 64;
;     bf16x8 Qf[4][2];
; #pragma unroll
;     for (int qt = 0; qt < 4; ++qt)
; #pragma unroll
;         for (int ks = 0; ks < 2; ++ks) Qf[qt][ks] = *(const bf16x8*)(U + (rowq + 16 * qt + fr) * NU + 1024 + h * 64 + 32 * ks + 8 * fq);
;     f32x4 ot[4][4];
; #pragma unroll
;     for (int dt = 0; dt < 4; ++dt)
; #pragma unroll
;         for (int qt = 0; qt < 4; ++qt) ot[dt][qt] = (f32x4){0.f, 0.f, 0.f, 0.f};
;     float carry[4] = {1.f, 1.f, 1.f, 1.f};
;     const bf16* Kbase = U + ((size_t)b * SEQ + 8 * (fr >> 2) + (fr & 3)) * NU + 1536 + h * 64 + 8 * fq;
;     const bf16* Vbase = VT + ((size_t)(b * 8 + h) * 64 + fr) * SEQ + 8 * fq;
;     bf16x8 Kn[2][2], Vn[4], Kf[2][2], Vf[4];
;     ...
;         const float cm = fmaxf(fmaxf(carry[0], carry[1]), fmaxf(carry[2], carry[3]));
;         if (__all(cm < 1.17549435e-38f)) break;
.LBB0_216:
.LBB0_217:
	v_and_b32_e32 v172, 15, v207
	v_mov_b32_e32 v179, 0
	v_lshlrev_b32_e32 v0, 1, v207
	v_and_b32_e32 v1, 3, v207
	v_lshlrev_b32_e32 v178, 14, v172
	v_and_or_b32 v186, v0, 24, v1
	v_lshl_add_u64 v[0:1], s[0:1], 0, v[178:179]
	v_and_b32_e32 v178, 48, v206
	v_lshl_add_u64 v[188:189], v[0:1], 0, v[178:179]
	v_mbcnt_lo_u32_b32 v0, -1, 0
	v_mbcnt_hi_u32_b32 v0, -1, v0
	v_and_b32_e32 v1, 48, v0
	v_cmp_eq_u32_e32 vcc, 48, v1
	v_readlane_b32 s2, v238, 1
	s_and_b32 s60, s2, 0xffffffc0
	v_cndmask_b32_e64 v1, 16, 0, vcc
	v_add_lshl_u32 v175, v1, v0, 2
	v_mov_b32_e32 v1, 0x80
	v_lshl_or_b32 v181, v0, 2, v1
	v_and_b32_e32 v1, 64, v0
	v_or_b32_e32 v2, v1, v172
	v_lshlrev_b32_e32 v183, 2, v2
	v_xor_b32_e32 v2, 16, v0
	v_add_u32_e32 v1, 64, v1
	s_add_i32 s10, 0, 0x20000
	v_cmp_lt_i32_e32 vcc, v2, v1
	s_lshl_b32 s0, s60, 2
	s_ashr_i32 s61, s60, 31
	v_cndmask_b32_e32 v2, v0, v2, vcc
	s_add_i32 s0, s0, s10
	v_lshlrev_b32_e32 v185, 2, v2
	v_xor_b32_e32 v2, 32, v0
	v_lshl_add_u32 v208, v206, 2, s0
	s_lshl_b64 s[0:1], s[60:61], 1
	v_cmp_lt_i32_e32 vcc, v2, v1
	s_add_u32 s0, s38, s0
	v_lshlrev_b32_e32 v176, 3, v173
	v_cndmask_b32_e32 v0, v0, v2, vcc
	v_lshlrev_b32_e32 v174, 2, v173
	s_addc_u32 s1, s39, s1
	s_mov_b32 s59, 0
	v_mov_b32_e32 v177, v179
	v_or_b32_e32 v180, 16, v172
	v_or_b32_e32 v182, 32, v172
	v_or_b32_e32 v184, 48, v206
	v_cmp_eq_u32_e64 s[2:3], 3, v173
	v_cmp_gt_u32_e64 s[4:5], 32, v206
	v_cmp_lt_u32_e64 s[6:7], v176, v172
	v_lshlrev_b32_e32 v187, 2, v0
	v_cmp_gt_u32_e64 s[8:9], 16, v206
	v_lshl_add_u32 v209, v172, 2, s10
	v_lshl_add_u64 v[190:191], s[0:1], 0, v[178:179]
	s_mov_b64 s[62:63], 0x40000
	s_mov_b64 s[64:65], 0x80000
	s_mov_b64 s[66:67], 0xc0000
	s_mov_b32 s23, 0x1f800000
	v_mov_b32_e32 v210, 0x358637bd
	s_mov_b32 s35, 0xf800000
	v_mov_b32_e32 v211, 0x260
	v_lshlrev_b32_e32 v178, 1, v174
	s_mov_b64 s[82:83], 0x8400
	s_mov_b32 s75, 0x8000
	s_mov_b64 s[84:85], 0x10400
	s_mov_b32 s97, 0x10000
	s_mov_b64 s[86:87], 0x18400
	s_mov_b32 s33, 0x18000
	s_mov_b32 s18, s96
	s_branch .LBB0_219
